# x sum-of-squares and W_q row reductions: xor-1/2/4/8 hops as DPP adds (quad_perm / row_half_mirror / row_mirror) instead of ds_bpermute, on top of static leading-half priority
# speedup vs baseline: 1.0033x; 1.0001x over previous
.LBB0_809:
	global_load_dwordx4 v[12:15], v[18:19], off offset:-3072
	global_load_dwordx4 v[0:3], v[18:19], off offset:-2048
	global_load_dwordx4 v[4:7], v[18:19], off offset:-1024
	global_load_dwordx4 v[8:11], v[18:19], off
	s_waitcnt vmcnt(3)
	v_mul_f32_e32 v26, v13, v13
	v_mul_f32_e32 v27, v15, v15
	s_waitcnt vmcnt(2)
	v_mul_f32_e32 v28, v1, v1
	v_mul_f32_e32 v29, v3, v3
	s_waitcnt vmcnt(1)
	v_mul_f32_e32 v30, v5, v5
	v_mul_f32_e32 v31, v7, v7
	v_fmac_f32_e32 v26, v12, v12
	v_fmac_f32_e32 v27, v14, v14
	v_fmac_f32_e32 v28, v0, v0
	v_fmac_f32_e32 v29, v2, v2
	s_waitcnt vmcnt(0)
	v_mul_f32_e32 v32, v9, v9
	v_mul_f32_e32 v33, v11, v11
	v_fmac_f32_e32 v30, v4, v4
	v_fmac_f32_e32 v31, v6, v6
	v_add_f32_e32 v26, v26, v27
	v_add_f32_e32 v27, v28, v29
	v_fmac_f32_e32 v32, v8, v8
	v_fmac_f32_e32 v33, v10, v10
	v_add_f32_e32 v28, v30, v31
	v_add_f32_e32 v26, v26, v27
	v_add_f32_e32 v26, v26, v28
	v_add_f32_e32 v27, v32, v33
	v_add_f32_e32 v26, v26, v27
	s_nop 1
	v_add_f32_dpp v26, v26, v26 quad_perm:[1,0,3,2] row_mask:0xf bank_mask:0xf
	s_nop 1
	v_add_f32_dpp v26, v26, v26 quad_perm:[2,3,0,1] row_mask:0xf bank_mask:0xf
	s_nop 1
	v_add_f32_dpp v26, v26, v26 row_half_mirror row_mask:0xf bank_mask:0xf
	s_nop 1
	v_add_f32_dpp v26, v26, v26 row_mirror row_mask:0xf bank_mask:0xf
	v_mov_b32_e32 v27, v26
	s_nop 1
	v_permlane16_swap_b32_e32 v27, v26
	s_waitcnt lgkmcnt(0)
	v_add_f32_e32 v26, v26, v27
	v_mov_b32_e32 v27, v26
	s_nop 1
	v_permlane32_swap_b32_e32 v27, v26
	s_and_saveexec_b64 s[0:1], s[40:41]
	s_cbranch_execz .LBB0_808
	s_waitcnt lgkmcnt(0)
	v_add_f32_e32 v26, v26, v27
	v_fmamk_f32 v26, v26, 0x3a800000, v250
	v_mul_f32_e32 v27, 0x4f800000, v26
	v_cmp_gt_f32_e32 vcc, s94, v26
	s_nop 1
	v_cndmask_b32_e32 v26, v26, v27, vcc
	v_sqrt_f32_e32 v27, v26
	s_nop 0
	v_add_u32_e32 v28, -1, v27
	v_fma_f32 v30, -v28, v27, v26
	v_add_u32_e32 v29, 1, v27
	v_cmp_ge_f32_e64 s[42:43], 0, v30
	s_nop 1
	v_cndmask_b32_e64 v28, v27, v28, s[42:43]
	v_fma_f32 v27, -v29, v27, v26
	v_cmp_lt_f32_e64 s[42:43], 0, v27
	s_nop 1
	v_cndmask_b32_e64 v27, v28, v29, s[42:43]
	v_mul_f32_e32 v28, 0x37800000, v27
	v_cndmask_b32_e32 v27, v27, v28, vcc
	v_cmp_class_f32_e32 vcc, v26, v251
	s_nop 1
	v_cndmask_b32_e32 v26, v27, v26, vcc
	v_div_scale_f32 v27, s[8:9], v26, v26, 1.0
	v_rcp_f32_e32 v28, v27
	s_add_u32 s8, s86, s4
	s_addc_u32 s9, s87, s5
	v_fma_f32 v29, -v27, v28, 1.0
	v_fmac_f32_e32 v28, v29, v28
	v_div_scale_f32 v29, vcc, 1.0, v26, 1.0
	v_mul_f32_e32 v30, v29, v28
	v_fma_f32 v31, -v27, v30, v29
	v_fmac_f32_e32 v30, v31, v28
	v_fma_f32 v27, -v27, v30, v29
	v_div_fmas_f32 v27, v27, v28, v30
	v_div_fixup_f32 v26, v27, v26, 1.0
	global_store_dword v141, v26, s[8:9]
	s_branch .LBB0_808

.Lxs_nopf:
	v_mul_f32_e32 v11, v11, v11
	v_mul_f32_e32 v13, v13, v13
	v_mul_f32_e32 v15, v15, v15
	v_mul_f32_e32 v17, v17, v17
	v_mul_f32_e32 v19, v19, v19
	v_mul_f32_e32 v21, v21, v21
	v_fmac_f32_e32 v11, v10, v10
	v_fmac_f32_e32 v13, v12, v12
	v_mul_f32_e32 v10, v27, v27
	v_mul_f32_e32 v12, v29, v29
	v_fmac_f32_e32 v15, v14, v14
	v_fmac_f32_e32 v17, v16, v16
	v_mul_f32_e32 v14, v31, v31
	v_mul_f32_e32 v16, v33, v33
	v_mul_f32_e32 v23, v23, v23
	v_mul_f32_e32 v25, v25, v25
	v_fmac_f32_e32 v19, v18, v18
	v_fmac_f32_e32 v21, v20, v20
	v_mul_f32_e32 v18, v35, v35
	v_mul_f32_e32 v20, v37, v37
	v_fmac_f32_e32 v10, v26, v26
	v_fmac_f32_e32 v12, v28, v28
	v_fmac_f32_e32 v14, v30, v30
	v_fmac_f32_e32 v16, v32, v32
	v_fmac_f32_e32 v23, v22, v22
	v_fmac_f32_e32 v25, v24, v24
	v_mul_f32_e32 v22, v39, v39
	v_mul_f32_e32 v24, v41, v41
	v_add_f32_e32 v11, v11, v13
	v_add_f32_e32 v13, v15, v17
	v_fmac_f32_e32 v18, v34, v34
	v_fmac_f32_e32 v20, v36, v36
	v_add_f32_e32 v10, v10, v12
	v_add_f32_e32 v12, v14, v16
	v_add_f32_e32 v15, v19, v21
	v_fmac_f32_e32 v22, v38, v38
	v_fmac_f32_e32 v24, v40, v40
	v_add_f32_e32 v11, v11, v13
	v_add_f32_e32 v13, v18, v20
	v_add_f32_e32 v10, v10, v12
	v_add_f32_e32 v17, v23, v25
	v_add_f32_e32 v14, v22, v24
	v_add_f32_e32 v11, v11, v15
	v_add_f32_e32 v10, v10, v13
	v_add_f32_e32 v11, v11, v17
	v_add_f32_e32 v10, v10, v14
	s_nop 1
	v_add_f32_dpp v11, v11, v11 quad_perm:[1,0,3,2] row_mask:0xf bank_mask:0xf
	v_add_f32_dpp v10, v10, v10 quad_perm:[1,0,3,2] row_mask:0xf bank_mask:0xf
	s_nop 1
	v_add_f32_dpp v11, v11, v11 quad_perm:[2,3,0,1] row_mask:0xf bank_mask:0xf
	v_add_f32_dpp v10, v10, v10 quad_perm:[2,3,0,1] row_mask:0xf bank_mask:0xf
	s_nop 1
	v_add_f32_dpp v11, v11, v11 row_half_mirror row_mask:0xf bank_mask:0xf
	v_add_f32_dpp v10, v10, v10 row_half_mirror row_mask:0xf bank_mask:0xf
	s_nop 1
	v_add_f32_dpp v11, v11, v11 row_mirror row_mask:0xf bank_mask:0xf
	v_add_f32_dpp v10, v10, v10 row_mirror row_mask:0xf bank_mask:0xf
	v_mov_b32_e32 v12, v11
	s_nop 1
	v_permlane16_swap_b32_e32 v12, v11
	v_mov_b32_e32 v14, v10
	s_nop 1
	v_permlane16_swap_b32_e32 v14, v10
	s_waitcnt lgkmcnt(1)
	v_add_f32_e32 v12, v11, v12
	s_waitcnt lgkmcnt(0)
	v_add_f32_e32 v10, v10, v14
	v_mov_b32_e32 v13, v12
	s_nop 1
	v_permlane32_swap_b32_e32 v13, v12
	v_mov_b32_e32 v11, v10
	s_nop 1
	v_permlane32_swap_b32_e32 v11, v10
	s_and_saveexec_b64 s[8:9], vcc
	s_cbranch_execz .LBB0_813
	s_waitcnt lgkmcnt(1)
	v_add_f32_e32 v12, v12, v13
	s_lshl_b64 s[10:11], s[6:7], 6
	v_cndmask_b32_e64 v14, 0, v12, s[40:41]
	v_lshl_add_u64 v[12:13], v[2:3], 0, s[10:11]
	s_cmp_eq_u32 s6, s0
	global_store_dword v[12:13], v14, off
	s_cbranch_scc1 .LBB0_813
	s_waitcnt lgkmcnt(0)
	v_add_f32_e32 v10, v10, v11
	s_lshl_b64 s[0:1], s[0:1], 6
	v_cndmask_b32_e64 v12, 0, v10, s[40:41]
	v_lshl_add_u64 v[10:11], v[2:3], 0, s[0:1]
	global_store_dword v[10:11], v12, off
	s_branch .LBB0_813
